# v12 + phase F mid-K rescale: row statistics prefetched one K-iteration ahead into free registers (no vmcnt(0) drains inside the GEMM loop)
# speedup vs baseline: 1.0051x; 1.0050x over previous
.LBB0_686:
	s_cmpk_lg_i32 s38, 0x700
	s_cbranch_scc1 .Lf_nopre
	global_load_dwordx2 v[238:239], v[132:133], off
	global_load_dwordx2 v[240:241], v[132:133], off offset:128
	global_load_dwordx2 v[242:243], v[132:133], off offset:256
	global_load_dwordx2 v[244:245], v[132:133], off offset:384
	global_load_dwordx2 v[246:247], v[132:133], off offset:1024
	global_load_dwordx2 v[248:249], v[132:133], off offset:1152
	global_load_dwordx2 v[250:251], v[132:133], off offset:1280
	global_load_dwordx2 v[252:253], v[132:133], off offset:1408
.Lf_nopre:
	s_cmpk_lg_i32 s38, 0x800
	s_cbranch_scc1 .LBB0_685
	v_ffbh_u32_e32 v0, v239
	v_min_u32_e32 v0, 32, v0
	v_lshlrev_b64 v[2:3], v0, v[238:239]
	v_min_u32_e32 v2, 1, v2
	v_or_b32_e32 v2, v3, v2
	v_cvt_f32_u32_e32 v2, v2
	v_sub_u32_e32 v0, 32, v0
	v_ldexp_f32 v0, v2, v0
	v_mul_f32_e32 v0, 0x35800000, v0
	v_fmamk_f32 v0, v0, 0x3a800000, v232
	v_cmp_gt_f32_e32 vcc, s5, v0
	v_mul_f32_e32 v2, 0x4b800000, v0
	s_nop 0
	v_cndmask_b32_e32 v0, v0, v2, vcc
	v_rsq_f32_e32 v0, v0
	s_nop 0
	v_mul_f32_e32 v2, 0x45800000, v0
	v_cndmask_b32_e32 v0, v0, v2, vcc
	v_pk_mul_f32 v[130:131], v[130:131], v[0:1] op_sel_hi:[1,0]
	v_pk_mul_f32 v[128:129], v[128:129], v[0:1] op_sel_hi:[1,0]
	v_pk_mul_f32 v[126:127], v[126:127], v[0:1] op_sel_hi:[1,0]
	v_pk_mul_f32 v[124:125], v[124:125], v[0:1] op_sel_hi:[1,0]
	v_pk_mul_f32 v[122:123], v[122:123], v[0:1] op_sel_hi:[1,0]
	v_pk_mul_f32 v[120:121], v[120:121], v[0:1] op_sel_hi:[1,0]
	v_pk_mul_f32 v[118:119], v[118:119], v[0:1] op_sel_hi:[1,0]
	v_pk_mul_f32 v[116:117], v[116:117], v[0:1] op_sel_hi:[1,0]
	v_ffbh_u32_e32 v0, v241
	v_min_u32_e32 v0, 32, v0
	v_lshlrev_b64 v[2:3], v0, v[240:241]
	v_min_u32_e32 v2, 1, v2
	v_or_b32_e32 v2, v3, v2
	v_cvt_f32_u32_e32 v2, v2
	v_sub_u32_e32 v0, 32, v0
	v_ldexp_f32 v0, v2, v0
	v_mul_f32_e32 v0, 0x35800000, v0
	v_fmamk_f32 v0, v0, 0x3a800000, v232
	v_cmp_gt_f32_e32 vcc, s5, v0
	v_mul_f32_e32 v2, 0x4b800000, v0
	s_nop 0
	v_cndmask_b32_e32 v0, v0, v2, vcc
	v_rsq_f32_e32 v0, v0
	s_nop 0
	v_mul_f32_e32 v2, 0x45800000, v0
	v_cndmask_b32_e32 v0, v0, v2, vcc
	v_pk_mul_f32 v[114:115], v[114:115], v[0:1] op_sel_hi:[1,0]
	v_pk_mul_f32 v[112:113], v[112:113], v[0:1] op_sel_hi:[1,0]
	v_pk_mul_f32 v[110:111], v[110:111], v[0:1] op_sel_hi:[1,0]
	v_pk_mul_f32 v[108:109], v[108:109], v[0:1] op_sel_hi:[1,0]
	v_pk_mul_f32 v[106:107], v[106:107], v[0:1] op_sel_hi:[1,0]
	v_pk_mul_f32 v[104:105], v[104:105], v[0:1] op_sel_hi:[1,0]
	v_pk_mul_f32 v[102:103], v[102:103], v[0:1] op_sel_hi:[1,0]
	v_pk_mul_f32 v[100:101], v[100:101], v[0:1] op_sel_hi:[1,0]
	v_ffbh_u32_e32 v0, v243
	v_min_u32_e32 v0, 32, v0
	v_lshlrev_b64 v[2:3], v0, v[242:243]
	v_min_u32_e32 v2, 1, v2
	v_or_b32_e32 v2, v3, v2
	v_cvt_f32_u32_e32 v2, v2
	v_sub_u32_e32 v0, 32, v0
	v_ldexp_f32 v0, v2, v0
	v_mul_f32_e32 v0, 0x35800000, v0
	v_fmamk_f32 v0, v0, 0x3a800000, v232
	v_cmp_gt_f32_e32 vcc, s5, v0
	v_mul_f32_e32 v2, 0x4b800000, v0
	s_nop 0
	v_cndmask_b32_e32 v0, v0, v2, vcc
	v_rsq_f32_e32 v0, v0
	s_nop 0
	v_mul_f32_e32 v2, 0x45800000, v0
	v_cndmask_b32_e32 v0, v0, v2, vcc
	v_pk_mul_f32 v[98:99], v[98:99], v[0:1] op_sel_hi:[1,0]
	v_pk_mul_f32 v[96:97], v[96:97], v[0:1] op_sel_hi:[1,0]
	v_pk_mul_f32 v[94:95], v[94:95], v[0:1] op_sel_hi:[1,0]
	v_pk_mul_f32 v[92:93], v[92:93], v[0:1] op_sel_hi:[1,0]
	v_pk_mul_f32 v[90:91], v[90:91], v[0:1] op_sel_hi:[1,0]
	v_pk_mul_f32 v[88:89], v[88:89], v[0:1] op_sel_hi:[1,0]
	v_pk_mul_f32 v[86:87], v[86:87], v[0:1] op_sel_hi:[1,0]
	v_pk_mul_f32 v[84:85], v[84:85], v[0:1] op_sel_hi:[1,0]
	v_ffbh_u32_e32 v0, v245
	v_min_u32_e32 v0, 32, v0
	v_lshlrev_b64 v[2:3], v0, v[244:245]
	v_min_u32_e32 v2, 1, v2
	v_or_b32_e32 v2, v3, v2
	v_cvt_f32_u32_e32 v2, v2
	v_sub_u32_e32 v0, 32, v0
	v_ldexp_f32 v0, v2, v0
	v_mul_f32_e32 v0, 0x35800000, v0
	v_fmamk_f32 v0, v0, 0x3a800000, v232
	v_cmp_gt_f32_e32 vcc, s5, v0
	v_mul_f32_e32 v2, 0x4b800000, v0
	s_nop 0
	v_cndmask_b32_e32 v0, v0, v2, vcc
	v_rsq_f32_e32 v0, v0
	s_nop 0
	v_mul_f32_e32 v2, 0x45800000, v0
	v_cndmask_b32_e32 v0, v0, v2, vcc
	v_pk_mul_f32 v[82:83], v[82:83], v[0:1] op_sel_hi:[1,0]
	v_pk_mul_f32 v[80:81], v[80:81], v[0:1] op_sel_hi:[1,0]
	v_pk_mul_f32 v[78:79], v[78:79], v[0:1] op_sel_hi:[1,0]
	v_pk_mul_f32 v[76:77], v[76:77], v[0:1] op_sel_hi:[1,0]
	v_pk_mul_f32 v[74:75], v[74:75], v[0:1] op_sel_hi:[1,0]
	v_pk_mul_f32 v[72:73], v[72:73], v[0:1] op_sel_hi:[1,0]
	v_pk_mul_f32 v[70:71], v[70:71], v[0:1] op_sel_hi:[1,0]
	v_pk_mul_f32 v[68:69], v[68:69], v[0:1] op_sel_hi:[1,0]
	v_ffbh_u32_e32 v0, v247
	v_min_u32_e32 v0, 32, v0
	v_lshlrev_b64 v[2:3], v0, v[246:247]
	v_min_u32_e32 v2, 1, v2
	v_or_b32_e32 v2, v3, v2
	v_cvt_f32_u32_e32 v2, v2
	v_sub_u32_e32 v0, 32, v0
	v_ldexp_f32 v0, v2, v0
	v_mul_f32_e32 v0, 0x35800000, v0
	v_fmamk_f32 v0, v0, 0x3a800000, v232
	v_cmp_gt_f32_e32 vcc, s5, v0
	v_mul_f32_e32 v2, 0x4b800000, v0
	s_nop 0
	v_cndmask_b32_e32 v0, v0, v2, vcc
	v_rsq_f32_e32 v0, v0
	s_nop 0
	v_mul_f32_e32 v2, 0x45800000, v0
	v_cndmask_b32_e32 v0, v0, v2, vcc
	v_pk_mul_f32 v[66:67], v[66:67], v[0:1] op_sel_hi:[1,0]
	v_pk_mul_f32 v[64:65], v[64:65], v[0:1] op_sel_hi:[1,0]
	v_pk_mul_f32 v[62:63], v[62:63], v[0:1] op_sel_hi:[1,0]
	v_pk_mul_f32 v[60:61], v[60:61], v[0:1] op_sel_hi:[1,0]
	v_pk_mul_f32 v[58:59], v[58:59], v[0:1] op_sel_hi:[1,0]
	v_pk_mul_f32 v[56:57], v[56:57], v[0:1] op_sel_hi:[1,0]
	v_pk_mul_f32 v[54:55], v[54:55], v[0:1] op_sel_hi:[1,0]
	v_pk_mul_f32 v[52:53], v[52:53], v[0:1] op_sel_hi:[1,0]
	v_ffbh_u32_e32 v0, v249
	v_min_u32_e32 v0, 32, v0
	v_lshlrev_b64 v[2:3], v0, v[248:249]
	v_min_u32_e32 v2, 1, v2
	v_or_b32_e32 v2, v3, v2
	v_cvt_f32_u32_e32 v2, v2
	v_sub_u32_e32 v0, 32, v0
	v_ldexp_f32 v0, v2, v0
	v_mul_f32_e32 v0, 0x35800000, v0
	v_fmamk_f32 v0, v0, 0x3a800000, v232
	v_cmp_gt_f32_e32 vcc, s5, v0
	v_mul_f32_e32 v2, 0x4b800000, v0
	s_nop 0
	v_cndmask_b32_e32 v0, v0, v2, vcc
	v_rsq_f32_e32 v0, v0
	s_nop 0
	v_mul_f32_e32 v2, 0x45800000, v0
	v_cndmask_b32_e32 v0, v0, v2, vcc
	v_pk_mul_f32 v[50:51], v[50:51], v[0:1] op_sel_hi:[1,0]
	v_pk_mul_f32 v[48:49], v[48:49], v[0:1] op_sel_hi:[1,0]
	v_pk_mul_f32 v[46:47], v[46:47], v[0:1] op_sel_hi:[1,0]
	v_pk_mul_f32 v[44:45], v[44:45], v[0:1] op_sel_hi:[1,0]
	v_pk_mul_f32 v[42:43], v[42:43], v[0:1] op_sel_hi:[1,0]
	v_pk_mul_f32 v[40:41], v[40:41], v[0:1] op_sel_hi:[1,0]
	v_pk_mul_f32 v[38:39], v[38:39], v[0:1] op_sel_hi:[1,0]
	v_pk_mul_f32 v[36:37], v[36:37], v[0:1] op_sel_hi:[1,0]
	v_ffbh_u32_e32 v0, v251
	v_min_u32_e32 v0, 32, v0
	v_lshlrev_b64 v[2:3], v0, v[250:251]
	v_min_u32_e32 v2, 1, v2
	v_or_b32_e32 v2, v3, v2
	v_cvt_f32_u32_e32 v2, v2
	v_sub_u32_e32 v0, 32, v0
	v_ldexp_f32 v0, v2, v0
	v_mul_f32_e32 v0, 0x35800000, v0
	v_fmamk_f32 v0, v0, 0x3a800000, v232
	v_cmp_gt_f32_e32 vcc, s5, v0
	v_mul_f32_e32 v2, 0x4b800000, v0
	s_nop 0
	v_cndmask_b32_e32 v0, v0, v2, vcc
	v_rsq_f32_e32 v0, v0
	s_nop 0
	v_mul_f32_e32 v2, 0x45800000, v0
	v_cndmask_b32_e32 v0, v0, v2, vcc
	v_pk_mul_f32 v[34:35], v[34:35], v[0:1] op_sel_hi:[1,0]
	v_pk_mul_f32 v[32:33], v[32:33], v[0:1] op_sel_hi:[1,0]
	v_pk_mul_f32 v[30:31], v[30:31], v[0:1] op_sel_hi:[1,0]
	v_pk_mul_f32 v[28:29], v[28:29], v[0:1] op_sel_hi:[1,0]
	v_pk_mul_f32 v[26:27], v[26:27], v[0:1] op_sel_hi:[1,0]
	v_pk_mul_f32 v[24:25], v[24:25], v[0:1] op_sel_hi:[1,0]
	v_pk_mul_f32 v[22:23], v[22:23], v[0:1] op_sel_hi:[1,0]
	v_pk_mul_f32 v[20:21], v[20:21], v[0:1] op_sel_hi:[1,0]
	v_ffbh_u32_e32 v0, v253
	v_min_u32_e32 v0, 32, v0
	v_lshlrev_b64 v[2:3], v0, v[252:253]
	v_min_u32_e32 v2, 1, v2
	v_or_b32_e32 v2, v3, v2
	v_cvt_f32_u32_e32 v2, v2
	v_sub_u32_e32 v0, 32, v0
	v_ldexp_f32 v0, v2, v0
	v_mul_f32_e32 v0, 0x35800000, v0
	v_fmamk_f32 v0, v0, 0x3a800000, v232
	v_cmp_gt_f32_e32 vcc, s5, v0
	v_mul_f32_e32 v2, 0x4b800000, v0
	s_nop 0
	v_cndmask_b32_e32 v0, v0, v2, vcc
	v_rsq_f32_e32 v0, v0
	s_nop 0
	v_mul_f32_e32 v2, 0x45800000, v0
	v_cndmask_b32_e32 v0, v0, v2, vcc
	v_pk_mul_f32 v[18:19], v[18:19], v[0:1] op_sel_hi:[1,0]
	v_pk_mul_f32 v[16:17], v[16:17], v[0:1] op_sel_hi:[1,0]
	v_pk_mul_f32 v[14:15], v[14:15], v[0:1] op_sel_hi:[1,0]
	v_pk_mul_f32 v[12:13], v[12:13], v[0:1] op_sel_hi:[1,0]
	v_pk_mul_f32 v[10:11], v[10:11], v[0:1] op_sel_hi:[1,0]
	v_pk_mul_f32 v[8:9], v[8:9], v[0:1] op_sel_hi:[1,0]
	v_pk_mul_f32 v[6:7], v[6:7], v[0:1] op_sel_hi:[1,0]
	v_pk_mul_f32 v[4:5], v[4:5], v[0:1] op_sel_hi:[1,0]
	s_branch .LBB0_685
